# grid barrier release flattened: waiting workgroups poll the global generation word directly (the per-XCD release hop is skipped) at all layer-loop seams
# speedup vs baseline: 1.0090x; 1.0020x over previous
.LBB0_490:
	v_readlane_b32 s16, v254, 54
	v_readlane_b32 s17, v254, 55
	v_cvt_f32_u32_e32 v0, v3
	v_sub_u32_e32 v5, 0, v3
	v_rcp_iflag_f32_e32 v0, v0
	s_nop 1
	global_atomic_add v4, v1, v236, s[16:17] sc0
	v_mul_f32_e32 v0, 0x4f7ffffe, v0
	v_cvt_u32_f32_e32 v0, v0
	v_mul_lo_u32 v5, v5, v0
	v_mul_hi_u32 v5, v0, v5
	v_add_u32_e32 v0, v0, v5
	s_waitcnt vmcnt(0)
	v_mul_hi_u32 v0, v4, v0
	v_mul_lo_u32 v5, v0, v3
	v_sub_u32_e32 v5, v4, v5
	v_add_u32_e32 v6, 1, v0
	v_cmp_ge_u32_e32 vcc, v5, v3
	v_add_u32_e32 v4, 1, v4
	s_nop 0
	v_cndmask_b32_e32 v0, v0, v6, vcc
	v_sub_u32_e32 v6, v5, v3
	v_cndmask_b32_e32 v5, v5, v6, vcc
	v_add_u32_e32 v6, 1, v0
	v_cmp_ge_u32_e32 vcc, v5, v3
	s_nop 1
	v_cndmask_b32_e32 v0, v0, v6, vcc
	v_mul_lo_u32 v5, v3, v0
	v_add_u32_e32 v3, v5, v3
	v_cmp_ne_u32_e32 vcc, v4, v3
	s_and_saveexec_b64 s[16:17], vcc
	s_xor_b64 s[16:17], exec, s[16:17]
	s_cbranch_execz .LBB0_504
	s_waitcnt lgkmcnt(0)
	global_load_dword v2, v1, s[80:81] sc1
	s_waitcnt vmcnt(0)
	v_cmp_eq_u32_e32 vcc, v2, v0
	s_and_saveexec_b64 s[18:19], vcc
	s_cbranch_execz .LBB0_503
	s_mov_b32 s1, 1
	s_mov_b64 s[22:23], 0
	s_branch .LBB0_494

.LBB0_633:
	v_readlane_b32 s14, v254, 54
	v_readlane_b32 s15, v254, 55
	v_cvt_f32_u32_e32 v0, v3
	v_sub_u32_e32 v5, 0, v3
	v_rcp_iflag_f32_e32 v0, v0
	s_nop 1
	global_atomic_add v4, v1, v236, s[14:15] sc0
	v_mul_f32_e32 v0, 0x4f7ffffe, v0
	v_cvt_u32_f32_e32 v0, v0
	v_mul_lo_u32 v5, v5, v0
	v_mul_hi_u32 v5, v0, v5
	v_add_u32_e32 v0, v0, v5
	s_waitcnt vmcnt(0)
	v_mul_hi_u32 v0, v4, v0
	v_mul_lo_u32 v5, v0, v3
	v_sub_u32_e32 v5, v4, v5
	v_add_u32_e32 v6, 1, v0
	v_cmp_ge_u32_e32 vcc, v5, v3
	v_add_u32_e32 v4, 1, v4
	s_nop 0
	v_cndmask_b32_e32 v0, v0, v6, vcc
	v_sub_u32_e32 v6, v5, v3
	v_cndmask_b32_e32 v5, v5, v6, vcc
	v_add_u32_e32 v6, 1, v0
	v_cmp_ge_u32_e32 vcc, v5, v3
	s_nop 1
	v_cndmask_b32_e32 v0, v0, v6, vcc
	v_mul_lo_u32 v5, v3, v0
	v_add_u32_e32 v3, v5, v3
	v_cmp_ne_u32_e32 vcc, v4, v3
	s_and_saveexec_b64 s[14:15], vcc
	s_xor_b64 s[14:15], exec, s[14:15]
	s_cbranch_execz .LBB0_647
	s_waitcnt lgkmcnt(0)
	global_load_dword v2, v1, s[80:81] sc1
	s_waitcnt vmcnt(0)
	v_cmp_eq_u32_e32 vcc, v2, v0
	s_and_saveexec_b64 s[16:17], vcc
	s_cbranch_execz .LBB0_646
	s_mov_b32 s1, 1
	s_mov_b64 s[22:23], 0
	s_branch .LBB0_637

.LBB0_841:
	v_readlane_b32 s0, v254, 54
	v_readlane_b32 s1, v254, 55
	v_cvt_f32_u32_e32 v0, v3
	v_sub_u32_e32 v5, 0, v3
	v_rcp_iflag_f32_e32 v0, v0
	s_nop 1
	global_atomic_add v4, v1, v236, s[0:1] sc0
	v_mul_f32_e32 v0, 0x4f7ffffe, v0
	v_cvt_u32_f32_e32 v0, v0
	v_mul_lo_u32 v5, v5, v0
	v_mul_hi_u32 v5, v0, v5
	v_add_u32_e32 v0, v0, v5
	s_waitcnt vmcnt(0)
	v_mul_hi_u32 v0, v4, v0
	v_mul_lo_u32 v5, v0, v3
	v_sub_u32_e32 v5, v4, v5
	v_add_u32_e32 v6, 1, v0
	v_cmp_ge_u32_e32 vcc, v5, v3
	v_add_u32_e32 v4, 1, v4
	s_nop 0
	v_cndmask_b32_e32 v0, v0, v6, vcc
	v_sub_u32_e32 v6, v5, v3
	v_cndmask_b32_e32 v5, v5, v6, vcc
	v_add_u32_e32 v6, 1, v0
	v_cmp_ge_u32_e32 vcc, v5, v3
	s_nop 1
	v_cndmask_b32_e32 v0, v0, v6, vcc
	v_mul_lo_u32 v5, v3, v0
	v_add_u32_e32 v3, v5, v3
	v_cmp_ne_u32_e32 vcc, v4, v3
	s_and_saveexec_b64 s[0:1], vcc
	s_xor_b64 s[14:15], exec, s[0:1]
	s_cbranch_execz .LBB0_855
	s_waitcnt lgkmcnt(0)
	global_load_dword v2, v1, s[80:81] sc1
	s_waitcnt vmcnt(0)
	v_cmp_eq_u32_e32 vcc, v2, v0
	s_and_saveexec_b64 s[16:17], vcc
	s_cbranch_execz .LBB0_854
	s_mov_b32 s0, 1
	s_mov_b64 s[18:19], 0
	s_branch .LBB0_845
